# v158 with the G1 K-loop head padded to a 64-byte boundary (other loop heads unchanged)
# speedup vs baseline: 1.0018x; 1.0018x over previous
.LBB0_268:
	s_or_b64 exec, exec, s[0:1]
	s_waitcnt vmcnt(13)
	v_mov_b32_e32 v8, v195
	s_cmpk_lt_i32 s2, 0x690
	s_waitcnt lgkmcnt(0)
	s_barrier
	s_nop 0
	s_nop 0
	s_nop 0
	s_nop 0
	s_nop 0
	s_nop 0
	s_nop 0
	s_nop 0
	s_nop 0
	s_cselect_b64 s[0:1], -1, 0
	s_cmpk_gt_i32 s2, 0x68f
	v_readfirstlane_b32 s42, v8
	s_cbranch_scc1 .LBB0_270
	s_ashr_i32 s3, s2, 31
	s_lshr_b32 s3, s3, 29
	s_add_i32 s3, s2, s3
	s_ashr_i32 s4, s3, 3
	s_and_b32 s3, s3, -8
	s_sub_i32 s3, s2, s3
	s_cmp_lt_i32 s3, 0
	s_movk_i32 s5, 0xd3
	s_cselect_b32 s5, s5, 0xd2
	s_mul_i32 s3, s3, s5
	s_add_i32 s3, s3, s4
	s_mul_hi_i32 s4, s3, 0x30c30c31
	s_lshr_b32 s5, s4, 31
	s_ashr_i32 s4, s4, 5
	s_add_i32 s4, s4, s5
	s_lshl_b32 s5, s4, 3
	s_mulk_i32 s4, 0xa8
	s_sub_i32 s3, s3, s4
	s_sext_i32_i16 s4, s3
	s_bfe_u32 s4, s4, 0x3001c
	s_add_i32 s4, s3, s4
	s_sext_i32_i16 s7, s4
	s_and_b32 s4, s4, 0xfff8
	s_sub_i32 s3, s3, s4
	s_sext_i32_i16 s3, s3
	s_add_i32 s6, s5, s3
	s_ashr_i32 s12, s7, 3
